# FFN-up gemm8 rewritten around direct HBM->LDS loads (global_load_lds_dwordx4, XOR-swizzled lane-linear LDS image, no staging VGPRs)
# speedup vs baseline: 1.0770x; 1.0265x over previous
.LBB0_1140:
	s_cmp_lt_i32 s88, 10
	s_cselect_b64 s[6:7], -1, 0
	s_and_b64 s[4:5], s[6:7], s[4:5]
	s_andn2_b64 vcc, exec, s[4:5]
	s_cbranch_vccnz .LBB0_1148
	s_cmpk_gt_i32 s2, 0x2bf
	s_cbranch_scc1 .LBB0_1148
	s_add_u32 s8, s34, 0x28c4000
	s_addc_u32 s9, s35, 0
	s_add_u32 s14, s34, 0x8a44000
	s_addc_u32 s15, s35, 0
	s_add_u32 s28, s34, 0x7a0000
	s_addc_u32 s29, s35, 0
	s_load_dword s31, s[0:1], 0x120
	v_readfirstlane_b32 s37, v205
	v_and_b32_e32 v192, 15, v204
	v_bfe_u32 v193, v204, 4, 2
	v_lshrrev_b32_e32 v194, 8, v204
	v_bfe_u32 v195, v204, 6, 2
	v_bfe_u32 v196, v204, 1, 3
	v_xor_b32_e32 v197, v193, v196
	v_xor_b32_e32 v198, 4, v197
	v_lshlrev_b32_e32 v197, 4, v197
	v_lshlrev_b32_e32 v198, 4, v198
	v_lshlrev_b32_e32 v199, 14, v194
	v_lshl_add_u32 v199, v192, 7, v199
	v_add_u32_e32 v242, v199, v197
	v_add_u32_e32 v243, v199, v198
	v_lshlrev_b32_e32 v199, 13, v195
	v_lshl_add_u32 v199, v192, 7, v199
	v_add_u32_e32 v199, 0x8000, v199
	v_add_u32_e32 v244, v199, v197
	v_add_u32_e32 v245, v199, v198
	v_add_u32_e32 v246, 0x10000, v242
	v_add_u32_e32 v248, 0x10000, v244
	v_add_u32_e32 v247, 0x10000, v243
	v_add_u32_e32 v249, 0x10000, v245
	v_lshrrev_b32_e32 v199, 3, v204
	v_and_b32_e32 v200, 7, v204
	v_bfe_u32 v201, v204, 4, 3
	v_xor_b32_e32 v200, v200, v201
	v_lshlrev_b32_e32 v200, 4, v200
	v_lshl_add_u32 v238, v199, 11, v200
	v_add_u32_e32 v239, 0x20000, v238
	v_add_u32_e32 v240, 0x40000, v238
	v_add_u32_e32 v241, 0x60000, v238
	s_lshl_b32 s38, s37, 10
	s_mov_b32 s36, s2
	s_and_b32 s4, s36, 7
	s_mulk_i32 s4, 0x58
	s_lshr_b32 s5, s36, 3
	s_add_i32 s4, s4, s5
	s_cmpk_ge_i32 s4, 176
	s_cselect_b32 s5, 1, 0
	s_cmpk_ge_i32 s4, 352
	s_cselect_b32 s19, 1, 0
	s_add_i32 s5, s5, s19
	s_cmpk_ge_i32 s4, 528
	s_cselect_b32 s19, 1, 0
	s_add_i32 s5, s5, s19
	s_mul_i32 s19, s5, 176
	s_sub_i32 s4, s4, s19
	s_and_b32 s19, s4, 7
	s_lshl_b32 s5, s5, 3
	s_add_i32 s5, s5, s19
	s_lshl_b32 s22, s5, 8
	s_lshr_b32 s4, s4, 3
	s_lshl_b32 s24, s4, 8
	s_lshl_b32 s19, s22, 11
	s_add_u32 s10, s14, s19
	s_addc_u32 s11, s15, 0
	s_lshl_b32 s19, s24, 11
	s_add_u32 s12, s28, s19
	s_addc_u32 s13, s29, 0
	s_waitcnt vmcnt(0) lgkmcnt(0)
	s_barrier
	s_add_u32 m0, s38, 0x0
	s_nop 0
	global_load_lds_dwordx4 v238, s[10:11]
	s_add_u32 m0, s38, 0x2000
	s_nop 0
	global_load_lds_dwordx4 v239, s[10:11]
	s_add_u32 m0, s38, 0x4000
	s_nop 0
	global_load_lds_dwordx4 v240, s[10:11]
	s_add_u32 m0, s38, 0x6000
	s_nop 0
	global_load_lds_dwordx4 v241, s[10:11]
	s_add_u32 m0, s38, 0x8000
	s_nop 0
	global_load_lds_dwordx4 v238, s[12:13]
	s_add_u32 m0, s38, 0xa000
	s_nop 0
	global_load_lds_dwordx4 v239, s[12:13]
	s_add_u32 m0, s38, 0xc000
	s_nop 0
	global_load_lds_dwordx4 v240, s[12:13]
	s_add_u32 m0, s38, 0xe000
	s_nop 0
	global_load_lds_dwordx4 v241, s[12:13]
	s_waitcnt vmcnt(0)
.Lgl_tile_f0:
	s_add_i32 s39, s36, s31
	s_cmpk_lt_i32 s39, 0x2c0
	s_cselect_b64 s[16:17], 0, -1
	s_cbranch_scc0 .Lgl_nonext_f0
	s_and_b32 s4, s39, 7
	s_mulk_i32 s4, 0x58
	s_lshr_b32 s5, s39, 3
	s_add_i32 s4, s4, s5
	s_cmpk_ge_i32 s4, 176
	s_cselect_b32 s5, 1, 0
	s_cmpk_ge_i32 s4, 352
	s_cselect_b32 s19, 1, 0
	s_add_i32 s5, s5, s19
	s_cmpk_ge_i32 s4, 528
	s_cselect_b32 s19, 1, 0
	s_add_i32 s5, s5, s19
	s_mul_i32 s19, s5, 176
	s_sub_i32 s4, s4, s19
	s_and_b32 s19, s4, 7
	s_lshl_b32 s5, s5, 3
	s_add_i32 s5, s5, s19
	s_lshl_b32 s18, s5, 8
	s_lshr_b32 s4, s4, 3
	s_lshl_b32 s20, s4, 8
	s_lshl_b32 s19, s18, 11
	s_add_u32 s26, s14, s19
	s_addc_u32 s27, s15, 0
	s_lshl_b32 s19, s20, 11
	s_add_u32 s46, s28, s19
	s_addc_u32 s47, s29, 0
	s_branch .Lgl_havenext_f0
.Lgl_nonext_f0:
	s_mov_b32 s18, s22
	s_mov_b32 s20, s24
	s_mov_b64 s[26:27], s[10:11]
	s_mov_b64 s[46:47], s[12:13]
.Lgl_havenext_f0:
	v_mov_b32_e32 v0, 0
	v_mov_b32_e32 v1, 0
	v_mov_b32_e32 v2, 0
	v_mov_b32_e32 v3, 0
	v_mov_b32_e32 v4, 0
	v_mov_b32_e32 v5, 0
	v_mov_b32_e32 v6, 0
	v_mov_b32_e32 v7, 0
	v_mov_b32_e32 v8, 0
	v_mov_b32_e32 v9, 0
	v_mov_b32_e32 v10, 0
	v_mov_b32_e32 v11, 0
	v_mov_b32_e32 v12, 0
	v_mov_b32_e32 v13, 0
	v_mov_b32_e32 v14, 0
	v_mov_b32_e32 v15, 0
	v_mov_b32_e32 v16, 0
	v_mov_b32_e32 v17, 0
	v_mov_b32_e32 v18, 0
	v_mov_b32_e32 v19, 0
	v_mov_b32_e32 v20, 0
	v_mov_b32_e32 v21, 0
	v_mov_b32_e32 v22, 0
	v_mov_b32_e32 v23, 0
	v_mov_b32_e32 v24, 0
	v_mov_b32_e32 v25, 0
	v_mov_b32_e32 v26, 0
	v_mov_b32_e32 v27, 0
	v_mov_b32_e32 v28, 0
	v_mov_b32_e32 v29, 0
	v_mov_b32_e32 v30, 0
	v_mov_b32_e32 v31, 0
	v_mov_b32_e32 v32, 0
	v_mov_b32_e32 v33, 0
	v_mov_b32_e32 v34, 0
	v_mov_b32_e32 v35, 0
	v_mov_b32_e32 v36, 0
	v_mov_b32_e32 v37, 0
	v_mov_b32_e32 v38, 0
	v_mov_b32_e32 v39, 0
	v_mov_b32_e32 v40, 0
	v_mov_b32_e32 v41, 0
	v_mov_b32_e32 v42, 0
	v_mov_b32_e32 v43, 0
	v_mov_b32_e32 v44, 0
	v_mov_b32_e32 v45, 0
	v_mov_b32_e32 v46, 0
	v_mov_b32_e32 v47, 0
	v_mov_b32_e32 v48, 0
	v_mov_b32_e32 v49, 0
	v_mov_b32_e32 v50, 0
	v_mov_b32_e32 v51, 0
	v_mov_b32_e32 v52, 0
	v_mov_b32_e32 v53, 0
	v_mov_b32_e32 v54, 0
	v_mov_b32_e32 v55, 0
	v_mov_b32_e32 v56, 0
	v_mov_b32_e32 v57, 0
	v_mov_b32_e32 v58, 0
	v_mov_b32_e32 v59, 0
	v_mov_b32_e32 v60, 0
	v_mov_b32_e32 v61, 0
	v_mov_b32_e32 v62, 0
	v_mov_b32_e32 v63, 0
	v_mov_b32_e32 v64, 0
	v_mov_b32_e32 v65, 0
	v_mov_b32_e32 v66, 0
	v_mov_b32_e32 v67, 0
	v_mov_b32_e32 v68, 0
	v_mov_b32_e32 v69, 0
	v_mov_b32_e32 v70, 0
	v_mov_b32_e32 v71, 0
	v_mov_b32_e32 v72, 0
	v_mov_b32_e32 v73, 0
	v_mov_b32_e32 v74, 0
	v_mov_b32_e32 v75, 0
	v_mov_b32_e32 v76, 0
	v_mov_b32_e32 v77, 0
	v_mov_b32_e32 v78, 0
	v_mov_b32_e32 v79, 0
	v_mov_b32_e32 v80, 0
	v_mov_b32_e32 v81, 0
	v_mov_b32_e32 v82, 0
	v_mov_b32_e32 v83, 0
	v_mov_b32_e32 v84, 0
	v_mov_b32_e32 v85, 0
	v_mov_b32_e32 v86, 0
	v_mov_b32_e32 v87, 0
	v_mov_b32_e32 v88, 0
	v_mov_b32_e32 v89, 0
	v_mov_b32_e32 v90, 0
	v_mov_b32_e32 v91, 0
	v_mov_b32_e32 v92, 0
	v_mov_b32_e32 v93, 0
	v_mov_b32_e32 v94, 0
	v_mov_b32_e32 v95, 0
	v_mov_b32_e32 v96, 0
	v_mov_b32_e32 v97, 0
	v_mov_b32_e32 v98, 0
	v_mov_b32_e32 v99, 0
	v_mov_b32_e32 v100, 0
	v_mov_b32_e32 v101, 0
	v_mov_b32_e32 v102, 0
	v_mov_b32_e32 v103, 0
	v_mov_b32_e32 v104, 0
	v_mov_b32_e32 v105, 0
	v_mov_b32_e32 v106, 0
	v_mov_b32_e32 v107, 0
	v_mov_b32_e32 v108, 0
	v_mov_b32_e32 v109, 0
	v_mov_b32_e32 v110, 0
	v_mov_b32_e32 v111, 0
	v_mov_b32_e32 v112, 0
	v_mov_b32_e32 v113, 0
	v_mov_b32_e32 v114, 0
	v_mov_b32_e32 v115, 0
	v_mov_b32_e32 v116, 0
	v_mov_b32_e32 v117, 0
	v_mov_b32_e32 v118, 0
	v_mov_b32_e32 v119, 0
	v_mov_b32_e32 v120, 0
	v_mov_b32_e32 v121, 0
	v_mov_b32_e32 v122, 0
	v_mov_b32_e32 v123, 0
	v_mov_b32_e32 v124, 0
	v_mov_b32_e32 v125, 0
	v_mov_b32_e32 v126, 0
	v_mov_b32_e32 v127, 0
	v_mov_b32_e32 v184, 0
	v_mov_b32_e32 v185, 0
	v_mov_b32_e32 v186, 0
	v_mov_b32_e32 v187, 0
	v_mov_b32_e32 v188, 0
	v_mov_b32_e32 v189, 0
	v_mov_b32_e32 v190, 0
	v_mov_b32_e32 v191, 0
	v_mov_b32_e32 v222, 0
	v_mov_b32_e32 v223, 0
	v_mov_b32_e32 v224, 0
	v_mov_b32_e32 v225, 0
	v_mov_b32_e32 v226, 0
	v_mov_b32_e32 v227, 0
	v_mov_b32_e32 v228, 0
	v_mov_b32_e32 v229, 0
	v_mov_b32_e32 v230, 0
	v_mov_b32_e32 v231, 0
	v_mov_b32_e32 v232, 0
	v_mov_b32_e32 v233, 0
	v_mov_b32_e32 v234, 0
	v_mov_b32_e32 v235, 0
	v_mov_b32_e32 v236, 0
	v_mov_b32_e32 v237, 0
	s_add_u32 s42, s10, 0x80
	s_addc_u32 s43, s11, 0
	s_add_u32 s44, s12, 0x80
	s_addc_u32 s45, s13, 0
	s_mov_b32 s40, 0
	s_waitcnt vmcnt(8)
	s_barrier
	s_branch .Lgl_kentry_f0
.Lgl_ktop_f0:
	s_waitcnt vmcnt(0)
	s_barrier
.Lgl_kentry_f0:
	s_setprio 1
	ds_read_b128 v[206:209], v244
	ds_read_b128 v[210:213], v244 offset:2048
	ds_read_b128 v[214:217], v244 offset:4096
	ds_read_b128 v[218:221], v244 offset:6144
	ds_read_b128 v[128:131], v242
	ds_read_b128 v[132:135], v242 offset:2048
	ds_read_b128 v[136:139], v242 offset:4096
	ds_read_b128 v[140:143], v242 offset:6144
	ds_read_b128 v[144:147], v242 offset:8192
	ds_read_b128 v[148:151], v242 offset:10240
	ds_read_b128 v[152:155], v242 offset:12288
	ds_read_b128 v[156:159], v242 offset:14336
	v_mfma_f32_16x16x32_bf16 v[96:99], v[222:225], v[184:187], v[96:99]
	v_mfma_f32_16x16x32_bf16 v[100:103], v[226:229], v[184:187], v[100:103]
	v_mfma_f32_16x16x32_bf16 v[104:107], v[230:233], v[184:187], v[104:107]
	v_mfma_f32_16x16x32_bf16 v[108:111], v[234:237], v[184:187], v[108:111]
	v_mfma_f32_16x16x32_bf16 v[112:115], v[222:225], v[188:191], v[112:115]
	v_mfma_f32_16x16x32_bf16 v[116:119], v[226:229], v[188:191], v[116:119]
	v_mfma_f32_16x16x32_bf16 v[120:123], v[230:233], v[188:191], v[120:123]
	v_mfma_f32_16x16x32_bf16 v[124:127], v[234:237], v[188:191], v[124:127]
	s_waitcnt lgkmcnt(7)
	v_mfma_f32_16x16x32_bf16 v[0:3], v[206:209], v[128:131], v[0:3]
	v_mfma_f32_16x16x32_bf16 v[4:7], v[210:213], v[128:131], v[4:7]
	v_mfma_f32_16x16x32_bf16 v[8:11], v[214:217], v[128:131], v[8:11]
	v_mfma_f32_16x16x32_bf16 v[12:15], v[218:221], v[128:131], v[12:15]
	s_add_u32 m0, s38, 0x10000
	s_nop 0
	global_load_lds_dwordx4 v238, s[42:43]
	s_add_u32 m0, s38, 0x12000
	s_nop 0
	global_load_lds_dwordx4 v239, s[42:43]
	ds_read_b128 v[222:225], v245
	ds_read_b128 v[226:229], v245 offset:2048
	s_waitcnt lgkmcnt(8)
	v_mfma_f32_16x16x32_bf16 v[16:19], v[206:209], v[132:135], v[16:19]
	v_mfma_f32_16x16x32_bf16 v[20:23], v[210:213], v[132:135], v[20:23]
	v_mfma_f32_16x16x32_bf16 v[24:27], v[214:217], v[132:135], v[24:27]
	v_mfma_f32_16x16x32_bf16 v[28:31], v[218:221], v[132:135], v[28:31]
	s_add_u32 m0, s38, 0x14000
	s_nop 0
	global_load_lds_dwordx4 v240, s[42:43]
	s_add_u32 m0, s38, 0x16000
	s_nop 0
	global_load_lds_dwordx4 v241, s[42:43]
	ds_read_b128 v[230:233], v245 offset:4096
	ds_read_b128 v[234:237], v245 offset:6144
	s_waitcnt lgkmcnt(9)
	v_mfma_f32_16x16x32_bf16 v[32:35], v[206:209], v[136:139], v[32:35]
	v_mfma_f32_16x16x32_bf16 v[36:39], v[210:213], v[136:139], v[36:39]
	v_mfma_f32_16x16x32_bf16 v[40:43], v[214:217], v[136:139], v[40:43]
	v_mfma_f32_16x16x32_bf16 v[44:47], v[218:221], v[136:139], v[44:47]
	s_add_u32 m0, s38, 0x18000
	s_nop 0
	global_load_lds_dwordx4 v238, s[44:45]
	s_add_u32 m0, s38, 0x1a000
	s_nop 0
	global_load_lds_dwordx4 v239, s[44:45]
	ds_read_b128 v[160:163], v243
	ds_read_b128 v[164:167], v243 offset:2048
	s_waitcnt lgkmcnt(10)
	v_mfma_f32_16x16x32_bf16 v[48:51], v[206:209], v[140:143], v[48:51]
	v_mfma_f32_16x16x32_bf16 v[52:55], v[210:213], v[140:143], v[52:55]
	v_mfma_f32_16x16x32_bf16 v[56:59], v[214:217], v[140:143], v[56:59]
	v_mfma_f32_16x16x32_bf16 v[60:63], v[218:221], v[140:143], v[60:63]
	s_add_u32 m0, s38, 0x1c000
	s_nop 0
	global_load_lds_dwordx4 v240, s[44:45]
	s_add_u32 m0, s38, 0x1e000
	s_nop 0
	global_load_lds_dwordx4 v241, s[44:45]
	ds_read_b128 v[168:171], v243 offset:4096
	ds_read_b128 v[172:175], v243 offset:6144
	s_waitcnt lgkmcnt(11)
	v_mfma_f32_16x16x32_bf16 v[64:67], v[206:209], v[144:147], v[64:67]
	v_mfma_f32_16x16x32_bf16 v[68:71], v[210:213], v[144:147], v[68:71]
	v_mfma_f32_16x16x32_bf16 v[72:75], v[214:217], v[144:147], v[72:75]
	v_mfma_f32_16x16x32_bf16 v[76:79], v[218:221], v[144:147], v[76:79]
	ds_read_b128 v[176:179], v243 offset:8192
	ds_read_b128 v[180:183], v243 offset:10240
	s_waitcnt lgkmcnt(12)
	v_mfma_f32_16x16x32_bf16 v[80:83], v[206:209], v[148:151], v[80:83]
	v_mfma_f32_16x16x32_bf16 v[84:87], v[210:213], v[148:151], v[84:87]
	v_mfma_f32_16x16x32_bf16 v[88:91], v[214:217], v[148:151], v[88:91]
	v_mfma_f32_16x16x32_bf16 v[92:95], v[218:221], v[148:151], v[92:95]
	ds_read_b128 v[184:187], v243 offset:12288
	ds_read_b128 v[188:191], v243 offset:14336
	s_waitcnt lgkmcnt(13)
	v_mfma_f32_16x16x32_bf16 v[96:99], v[206:209], v[152:155], v[96:99]
	v_mfma_f32_16x16x32_bf16 v[100:103], v[210:213], v[152:155], v[100:103]
	v_mfma_f32_16x16x32_bf16 v[104:107], v[214:217], v[152:155], v[104:107]
	v_mfma_f32_16x16x32_bf16 v[108:111], v[218:221], v[152:155], v[108:111]
	s_waitcnt lgkmcnt(12)
	v_mfma_f32_16x16x32_bf16 v[112:115], v[206:209], v[156:159], v[112:115]
	v_mfma_f32_16x16x32_bf16 v[116:119], v[210:213], v[156:159], v[116:119]
	v_mfma_f32_16x16x32_bf16 v[120:123], v[214:217], v[156:159], v[120:123]
	v_mfma_f32_16x16x32_bf16 v[124:127], v[218:221], v[156:159], v[124:127]
	s_waitcnt lgkmcnt(7)
	v_mfma_f32_16x16x32_bf16 v[0:3], v[222:225], v[160:163], v[0:3]
	v_mfma_f32_16x16x32_bf16 v[4:7], v[226:229], v[160:163], v[4:7]
	v_mfma_f32_16x16x32_bf16 v[8:11], v[230:233], v[160:163], v[8:11]
	v_mfma_f32_16x16x32_bf16 v[12:15], v[234:237], v[160:163], v[12:15]
	s_waitcnt lgkmcnt(6)
	v_mfma_f32_16x16x32_bf16 v[16:19], v[222:225], v[164:167], v[16:19]
	v_mfma_f32_16x16x32_bf16 v[20:23], v[226:229], v[164:167], v[20:23]
	v_mfma_f32_16x16x32_bf16 v[24:27], v[230:233], v[164:167], v[24:27]
	v_mfma_f32_16x16x32_bf16 v[28:31], v[234:237], v[164:167], v[28:31]
	s_waitcnt lgkmcnt(5)
	v_mfma_f32_16x16x32_bf16 v[32:35], v[222:225], v[168:171], v[32:35]
	v_mfma_f32_16x16x32_bf16 v[36:39], v[226:229], v[168:171], v[36:39]
	v_mfma_f32_16x16x32_bf16 v[40:43], v[230:233], v[168:171], v[40:43]
	v_mfma_f32_16x16x32_bf16 v[44:47], v[234:237], v[168:171], v[44:47]
	s_waitcnt lgkmcnt(4)
	v_mfma_f32_16x16x32_bf16 v[48:51], v[222:225], v[172:175], v[48:51]
	v_mfma_f32_16x16x32_bf16 v[52:55], v[226:229], v[172:175], v[52:55]
	v_mfma_f32_16x16x32_bf16 v[56:59], v[230:233], v[172:175], v[56:59]
	v_mfma_f32_16x16x32_bf16 v[60:63], v[234:237], v[172:175], v[60:63]
	s_waitcnt lgkmcnt(3)
	v_mfma_f32_16x16x32_bf16 v[64:67], v[222:225], v[176:179], v[64:67]
	v_mfma_f32_16x16x32_bf16 v[68:71], v[226:229], v[176:179], v[68:71]
	v_mfma_f32_16x16x32_bf16 v[72:75], v[230:233], v[176:179], v[72:75]
	v_mfma_f32_16x16x32_bf16 v[76:79], v[234:237], v[176:179], v[76:79]
	s_waitcnt lgkmcnt(2)
	v_mfma_f32_16x16x32_bf16 v[80:83], v[222:225], v[180:183], v[80:83]
	v_mfma_f32_16x16x32_bf16 v[84:87], v[226:229], v[180:183], v[84:87]
	v_mfma_f32_16x16x32_bf16 v[88:91], v[230:233], v[180:183], v[88:91]
	v_mfma_f32_16x16x32_bf16 v[92:95], v[234:237], v[180:183], v[92:95]
	s_setprio 0
	s_waitcnt vmcnt(0) lgkmcnt(0)
	s_barrier
	s_add_u32 s42, s42, 0x80
	s_addc_u32 s43, s43, 0
	s_add_u32 s44, s44, 0x80
	s_addc_u32 s45, s45, 0
	s_cmp_eq_u32 s40, 7
	s_cselect_b32 s48, s26, s42
	s_cselect_b32 s49, s27, s43
	s_cselect_b32 s50, s46, s44
	s_cselect_b32 s51, s47, s45
	s_setprio 1
	ds_read_b128 v[206:209], v248
	ds_read_b128 v[210:213], v248 offset:2048
	ds_read_b128 v[214:217], v248 offset:4096
	ds_read_b128 v[218:221], v248 offset:6144
	ds_read_b128 v[128:131], v246
	ds_read_b128 v[132:135], v246 offset:2048
	ds_read_b128 v[136:139], v246 offset:4096
	ds_read_b128 v[140:143], v246 offset:6144
	ds_read_b128 v[144:147], v246 offset:8192
	ds_read_b128 v[148:151], v246 offset:10240
	ds_read_b128 v[152:155], v246 offset:12288
	ds_read_b128 v[156:159], v246 offset:14336
	v_mfma_f32_16x16x32_bf16 v[96:99], v[222:225], v[184:187], v[96:99]
	v_mfma_f32_16x16x32_bf16 v[100:103], v[226:229], v[184:187], v[100:103]
	v_mfma_f32_16x16x32_bf16 v[104:107], v[230:233], v[184:187], v[104:107]
	v_mfma_f32_16x16x32_bf16 v[108:111], v[234:237], v[184:187], v[108:111]
	v_mfma_f32_16x16x32_bf16 v[112:115], v[222:225], v[188:191], v[112:115]
	v_mfma_f32_16x16x32_bf16 v[116:119], v[226:229], v[188:191], v[116:119]
	v_mfma_f32_16x16x32_bf16 v[120:123], v[230:233], v[188:191], v[120:123]
	v_mfma_f32_16x16x32_bf16 v[124:127], v[234:237], v[188:191], v[124:127]
	s_waitcnt lgkmcnt(7)
	v_mfma_f32_16x16x32_bf16 v[0:3], v[206:209], v[128:131], v[0:3]
	v_mfma_f32_16x16x32_bf16 v[4:7], v[210:213], v[128:131], v[4:7]
	v_mfma_f32_16x16x32_bf16 v[8:11], v[214:217], v[128:131], v[8:11]
	v_mfma_f32_16x16x32_bf16 v[12:15], v[218:221], v[128:131], v[12:15]
	s_add_u32 m0, s38, 0x0
	s_nop 0
	global_load_lds_dwordx4 v238, s[48:49]
	s_add_u32 m0, s38, 0x2000
	s_nop 0
	global_load_lds_dwordx4 v239, s[48:49]
	ds_read_b128 v[222:225], v249
	ds_read_b128 v[226:229], v249 offset:2048
	s_waitcnt lgkmcnt(8)
	v_mfma_f32_16x16x32_bf16 v[16:19], v[206:209], v[132:135], v[16:19]
	v_mfma_f32_16x16x32_bf16 v[20:23], v[210:213], v[132:135], v[20:23]
	v_mfma_f32_16x16x32_bf16 v[24:27], v[214:217], v[132:135], v[24:27]
	v_mfma_f32_16x16x32_bf16 v[28:31], v[218:221], v[132:135], v[28:31]
	s_add_u32 m0, s38, 0x4000
	s_nop 0
	global_load_lds_dwordx4 v240, s[48:49]
	s_add_u32 m0, s38, 0x6000
	s_nop 0
	global_load_lds_dwordx4 v241, s[48:49]
	ds_read_b128 v[230:233], v249 offset:4096
	ds_read_b128 v[234:237], v249 offset:6144
	s_waitcnt lgkmcnt(9)
	v_mfma_f32_16x16x32_bf16 v[32:35], v[206:209], v[136:139], v[32:35]
	v_mfma_f32_16x16x32_bf16 v[36:39], v[210:213], v[136:139], v[36:39]
	v_mfma_f32_16x16x32_bf16 v[40:43], v[214:217], v[136:139], v[40:43]
	v_mfma_f32_16x16x32_bf16 v[44:47], v[218:221], v[136:139], v[44:47]
	s_add_u32 m0, s38, 0x8000
	s_nop 0
	global_load_lds_dwordx4 v238, s[50:51]
	s_add_u32 m0, s38, 0xa000
	s_nop 0
	global_load_lds_dwordx4 v239, s[50:51]
	ds_read_b128 v[160:163], v247
	ds_read_b128 v[164:167], v247 offset:2048
	s_waitcnt lgkmcnt(10)
	v_mfma_f32_16x16x32_bf16 v[48:51], v[206:209], v[140:143], v[48:51]
	v_mfma_f32_16x16x32_bf16 v[52:55], v[210:213], v[140:143], v[52:55]
	v_mfma_f32_16x16x32_bf16 v[56:59], v[214:217], v[140:143], v[56:59]
	v_mfma_f32_16x16x32_bf16 v[60:63], v[218:221], v[140:143], v[60:63]
	s_add_u32 m0, s38, 0xc000
	s_nop 0
	global_load_lds_dwordx4 v240, s[50:51]
	s_add_u32 m0, s38, 0xe000
	s_nop 0
	global_load_lds_dwordx4 v241, s[50:51]
	ds_read_b128 v[168:171], v247 offset:4096
	ds_read_b128 v[172:175], v247 offset:6144
	s_waitcnt lgkmcnt(11)
	v_mfma_f32_16x16x32_bf16 v[64:67], v[206:209], v[144:147], v[64:67]
	v_mfma_f32_16x16x32_bf16 v[68:71], v[210:213], v[144:147], v[68:71]
	v_mfma_f32_16x16x32_bf16 v[72:75], v[214:217], v[144:147], v[72:75]
	v_mfma_f32_16x16x32_bf16 v[76:79], v[218:221], v[144:147], v[76:79]
	ds_read_b128 v[176:179], v247 offset:8192
	ds_read_b128 v[180:183], v247 offset:10240
	s_waitcnt lgkmcnt(12)
	v_mfma_f32_16x16x32_bf16 v[80:83], v[206:209], v[148:151], v[80:83]
	v_mfma_f32_16x16x32_bf16 v[84:87], v[210:213], v[148:151], v[84:87]
	v_mfma_f32_16x16x32_bf16 v[88:91], v[214:217], v[148:151], v[88:91]
	v_mfma_f32_16x16x32_bf16 v[92:95], v[218:221], v[148:151], v[92:95]
	ds_read_b128 v[184:187], v247 offset:12288
	ds_read_b128 v[188:191], v247 offset:14336
	s_waitcnt lgkmcnt(13)
	v_mfma_f32_16x16x32_bf16 v[96:99], v[206:209], v[152:155], v[96:99]
	v_mfma_f32_16x16x32_bf16 v[100:103], v[210:213], v[152:155], v[100:103]
	v_mfma_f32_16x16x32_bf16 v[104:107], v[214:217], v[152:155], v[104:107]
	v_mfma_f32_16x16x32_bf16 v[108:111], v[218:221], v[152:155], v[108:111]
	s_waitcnt lgkmcnt(12)
	v_mfma_f32_16x16x32_bf16 v[112:115], v[206:209], v[156:159], v[112:115]
	v_mfma_f32_16x16x32_bf16 v[116:119], v[210:213], v[156:159], v[116:119]
	v_mfma_f32_16x16x32_bf16 v[120:123], v[214:217], v[156:159], v[120:123]
	v_mfma_f32_16x16x32_bf16 v[124:127], v[218:221], v[156:159], v[124:127]
	s_waitcnt lgkmcnt(7)
	v_mfma_f32_16x16x32_bf16 v[0:3], v[222:225], v[160:163], v[0:3]
	v_mfma_f32_16x16x32_bf16 v[4:7], v[226:229], v[160:163], v[4:7]
	v_mfma_f32_16x16x32_bf16 v[8:11], v[230:233], v[160:163], v[8:11]
	v_mfma_f32_16x16x32_bf16 v[12:15], v[234:237], v[160:163], v[12:15]
	s_waitcnt lgkmcnt(6)
	v_mfma_f32_16x16x32_bf16 v[16:19], v[222:225], v[164:167], v[16:19]
	v_mfma_f32_16x16x32_bf16 v[20:23], v[226:229], v[164:167], v[20:23]
	v_mfma_f32_16x16x32_bf16 v[24:27], v[230:233], v[164:167], v[24:27]
	v_mfma_f32_16x16x32_bf16 v[28:31], v[234:237], v[164:167], v[28:31]
	s_waitcnt lgkmcnt(5)
	v_mfma_f32_16x16x32_bf16 v[32:35], v[222:225], v[168:171], v[32:35]
	v_mfma_f32_16x16x32_bf16 v[36:39], v[226:229], v[168:171], v[36:39]
	v_mfma_f32_16x16x32_bf16 v[40:43], v[230:233], v[168:171], v[40:43]
	v_mfma_f32_16x16x32_bf16 v[44:47], v[234:237], v[168:171], v[44:47]
	s_waitcnt lgkmcnt(4)
	v_mfma_f32_16x16x32_bf16 v[48:51], v[222:225], v[172:175], v[48:51]
	v_mfma_f32_16x16x32_bf16 v[52:55], v[226:229], v[172:175], v[52:55]
	v_mfma_f32_16x16x32_bf16 v[56:59], v[230:233], v[172:175], v[56:59]
	v_mfma_f32_16x16x32_bf16 v[60:63], v[234:237], v[172:175], v[60:63]
	s_waitcnt lgkmcnt(3)
	v_mfma_f32_16x16x32_bf16 v[64:67], v[222:225], v[176:179], v[64:67]
	v_mfma_f32_16x16x32_bf16 v[68:71], v[226:229], v[176:179], v[68:71]
	v_mfma_f32_16x16x32_bf16 v[72:75], v[230:233], v[176:179], v[72:75]
	v_mfma_f32_16x16x32_bf16 v[76:79], v[234:237], v[176:179], v[76:79]
	s_waitcnt lgkmcnt(2)
	v_mfma_f32_16x16x32_bf16 v[80:83], v[222:225], v[180:183], v[80:83]
	v_mfma_f32_16x16x32_bf16 v[84:87], v[226:229], v[180:183], v[84:87]
	v_mfma_f32_16x16x32_bf16 v[88:91], v[230:233], v[180:183], v[88:91]
	v_mfma_f32_16x16x32_bf16 v[92:95], v[234:237], v[180:183], v[92:95]
	s_setprio 0
	s_waitcnt lgkmcnt(0)
	s_add_u32 s42, s42, 0x80
	s_addc_u32 s43, s43, 0
	s_add_u32 s44, s44, 0x80
	s_addc_u32 s45, s45, 0
	s_add_i32 s40, s40, 1
	s_cmp_lt_u32 s40, 8
	s_cbranch_scc1 .Lgl_ktop_f0
	v_mfma_f32_16x16x32_bf16 v[96:99], v[222:225], v[184:187], v[96:99]
	v_mfma_f32_16x16x32_bf16 v[100:103], v[226:229], v[184:187], v[100:103]
	v_mfma_f32_16x16x32_bf16 v[104:107], v[230:233], v[184:187], v[104:107]
	v_mfma_f32_16x16x32_bf16 v[108:111], v[234:237], v[184:187], v[108:111]
	v_mfma_f32_16x16x32_bf16 v[112:115], v[222:225], v[188:191], v[112:115]
	v_mfma_f32_16x16x32_bf16 v[116:119], v[226:229], v[188:191], v[116:119]
	v_mfma_f32_16x16x32_bf16 v[120:123], v[230:233], v[188:191], v[120:123]
	v_mfma_f32_16x16x32_bf16 v[124:127], v[234:237], v[188:191], v[124:127]
	s_mul_i32 s98, s22, 0x1600
	s_add_u32 s98, s98, s24
	s_add_u32 s100, s8, s98
	s_addc_u32 s101, s9, 0
	v_and_b32_e32 v168, 15, v204
	v_lshrrev_b32_e32 v169, 8, v204
	v_lshl_add_u32 v168, v169, 7, v168
	v_mul_u32_u24_e32 v168, 0x1600, v168
	v_and_b32_e32 v169, 0xc0, v204
	v_add_u32_e32 v168, v168, v169
	v_bfe_u32 v169, v204, 4, 1
	v_lshl_add_u32 v168, v169, 5, v168
	v_bfe_u32 v169, v204, 5, 1
	v_lshl_add_u32 v168, v169, 4, v168
	s_nop 7
	s_nop 7
	v_mul_f32_e32 v160, 0xbfb8aa3b, v0
	v_mul_f32_e32 v161, 0xbfb8aa3b, v1
	v_mul_f32_e32 v162, 0xbfb8aa3b, v2
	v_mul_f32_e32 v163, 0xbfb8aa3b, v3
	v_mul_f32_e32 v164, 0xbfb8aa3b, v8
	v_mul_f32_e32 v165, 0xbfb8aa3b, v9
	v_mul_f32_e32 v166, 0xbfb8aa3b, v10
	v_mul_f32_e32 v167, 0xbfb8aa3b, v11
	v_exp_f32_e32 v160, v160
	v_exp_f32_e32 v161, v161
	v_exp_f32_e32 v162, v162
	v_exp_f32_e32 v163, v163
	v_exp_f32_e32 v164, v164
	v_exp_f32_e32 v165, v165
	v_exp_f32_e32 v166, v166
	v_exp_f32_e32 v167, v167
	v_add_f32_e32 v160, 1.0, v160
	v_add_f32_e32 v161, 1.0, v161
	v_add_f32_e32 v162, 1.0, v162
	v_add_f32_e32 v163, 1.0, v163
	v_add_f32_e32 v164, 1.0, v164
	v_add_f32_e32 v165, 1.0, v165
	v_add_f32_e32 v166, 1.0, v166
	v_add_f32_e32 v167, 1.0, v167
	v_rcp_f32_e32 v160, v160
	v_rcp_f32_e32 v161, v161
	v_rcp_f32_e32 v162, v162
	v_rcp_f32_e32 v163, v163
	v_rcp_f32_e32 v164, v164
	v_rcp_f32_e32 v165, v165
	v_rcp_f32_e32 v166, v166
	v_rcp_f32_e32 v167, v167
	v_mul_f32_e32 v0, v0, v160
	v_mul_f32_e32 v1, v1, v161
	v_mul_f32_e32 v2, v2, v162
	v_mul_f32_e32 v3, v3, v163
	v_mul_f32_e32 v8, v8, v164
	v_mul_f32_e32 v9, v9, v165
	v_mul_f32_e32 v10, v10, v166
	v_mul_f32_e32 v11, v11, v167
	v_mul_f32_e32 v4, v0, v4
	v_mul_f32_e32 v5, v1, v5
	v_mul_f32_e32 v6, v2, v6
	v_mul_f32_e32 v7, v3, v7
	v_mul_f32_e32 v12, v8, v12
	v_mul_f32_e32 v13, v9, v13
	v_mul_f32_e32 v14, v10, v14
	v_mul_f32_e32 v15, v11, v15
	v_cvt_pk_bf16_f32 v0, v4, v5
	v_cvt_pk_bf16_f32 v1, v6, v7
	v_cvt_pk_bf16_f32 v2, v12, v13
	v_cvt_pk_bf16_f32 v3, v14, v15
	s_nop 1
	v_permlane16_swap_b32_e32 v0, v2
	v_permlane16_swap_b32_e32 v1, v3
	global_store_dwordx4 v168, v[0:3], s[100:101] sc1
	s_add_u32 s100, s100, 0x16000
	s_addc_u32 s101, s101, 0
	v_mul_f32_e32 v160, 0xbfb8aa3b, v16
	v_mul_f32_e32 v161, 0xbfb8aa3b, v17
	v_mul_f32_e32 v162, 0xbfb8aa3b, v18
	v_mul_f32_e32 v163, 0xbfb8aa3b, v19
	v_mul_f32_e32 v164, 0xbfb8aa3b, v24
	v_mul_f32_e32 v165, 0xbfb8aa3b, v25
	v_mul_f32_e32 v166, 0xbfb8aa3b, v26
	v_mul_f32_e32 v167, 0xbfb8aa3b, v27
	v_exp_f32_e32 v160, v160
	v_exp_f32_e32 v161, v161
	v_exp_f32_e32 v162, v162
	v_exp_f32_e32 v163, v163
	v_exp_f32_e32 v164, v164
	v_exp_f32_e32 v165, v165
	v_exp_f32_e32 v166, v166
	v_exp_f32_e32 v167, v167
	v_add_f32_e32 v160, 1.0, v160
	v_add_f32_e32 v161, 1.0, v161
	v_add_f32_e32 v162, 1.0, v162
	v_add_f32_e32 v163, 1.0, v163
	v_add_f32_e32 v164, 1.0, v164
	v_add_f32_e32 v165, 1.0, v165
	v_add_f32_e32 v166, 1.0, v166
	v_add_f32_e32 v167, 1.0, v167
	v_rcp_f32_e32 v160, v160
	v_rcp_f32_e32 v161, v161
	v_rcp_f32_e32 v162, v162
	v_rcp_f32_e32 v163, v163
	v_rcp_f32_e32 v164, v164
	v_rcp_f32_e32 v165, v165
	v_rcp_f32_e32 v166, v166
	v_rcp_f32_e32 v167, v167
	v_mul_f32_e32 v16, v16, v160
	v_mul_f32_e32 v17, v17, v161
	v_mul_f32_e32 v18, v18, v162
	v_mul_f32_e32 v19, v19, v163
	v_mul_f32_e32 v24, v24, v164
	v_mul_f32_e32 v25, v25, v165
	v_mul_f32_e32 v26, v26, v166
	v_mul_f32_e32 v27, v27, v167
	v_mul_f32_e32 v20, v16, v20
	v_mul_f32_e32 v21, v17, v21
	v_mul_f32_e32 v22, v18, v22
	v_mul_f32_e32 v23, v19, v23
	v_mul_f32_e32 v28, v24, v28
	v_mul_f32_e32 v29, v25, v29
	v_mul_f32_e32 v30, v26, v30
	v_mul_f32_e32 v31, v27, v31
	v_cvt_pk_bf16_f32 v16, v20, v21
	v_cvt_pk_bf16_f32 v17, v22, v23
	v_cvt_pk_bf16_f32 v18, v28, v29
	v_cvt_pk_bf16_f32 v19, v30, v31
	s_nop 1
	v_permlane16_swap_b32_e32 v16, v18
	v_permlane16_swap_b32_e32 v17, v19
	global_store_dwordx4 v168, v[16:19], s[100:101] sc1
	s_add_u32 s100, s100, 0x16000
	s_addc_u32 s101, s101, 0
	v_mul_f32_e32 v160, 0xbfb8aa3b, v32
	v_mul_f32_e32 v161, 0xbfb8aa3b, v33
	v_mul_f32_e32 v162, 0xbfb8aa3b, v34
	v_mul_f32_e32 v163, 0xbfb8aa3b, v35
	v_mul_f32_e32 v164, 0xbfb8aa3b, v40
	v_mul_f32_e32 v165, 0xbfb8aa3b, v41
	v_mul_f32_e32 v166, 0xbfb8aa3b, v42
	v_mul_f32_e32 v167, 0xbfb8aa3b, v43
	v_exp_f32_e32 v160, v160
	v_exp_f32_e32 v161, v161
	v_exp_f32_e32 v162, v162
	v_exp_f32_e32 v163, v163
	v_exp_f32_e32 v164, v164
	v_exp_f32_e32 v165, v165
	v_exp_f32_e32 v166, v166
	v_exp_f32_e32 v167, v167
	v_add_f32_e32 v160, 1.0, v160
	v_add_f32_e32 v161, 1.0, v161
	v_add_f32_e32 v162, 1.0, v162
	v_add_f32_e32 v163, 1.0, v163
	v_add_f32_e32 v164, 1.0, v164
	v_add_f32_e32 v165, 1.0, v165
	v_add_f32_e32 v166, 1.0, v166
	v_add_f32_e32 v167, 1.0, v167
	v_rcp_f32_e32 v160, v160
	v_rcp_f32_e32 v161, v161
	v_rcp_f32_e32 v162, v162
	v_rcp_f32_e32 v163, v163
	v_rcp_f32_e32 v164, v164
	v_rcp_f32_e32 v165, v165
	v_rcp_f32_e32 v166, v166
	v_rcp_f32_e32 v167, v167
	v_mul_f32_e32 v32, v32, v160
	v_mul_f32_e32 v33, v33, v161
	v_mul_f32_e32 v34, v34, v162
	v_mul_f32_e32 v35, v35, v163
	v_mul_f32_e32 v40, v40, v164
	v_mul_f32_e32 v41, v41, v165
	v_mul_f32_e32 v42, v42, v166
	v_mul_f32_e32 v43, v43, v167
	v_mul_f32_e32 v36, v32, v36
	v_mul_f32_e32 v37, v33, v37
	v_mul_f32_e32 v38, v34, v38
	v_mul_f32_e32 v39, v35, v39
	v_mul_f32_e32 v44, v40, v44
	v_mul_f32_e32 v45, v41, v45
	v_mul_f32_e32 v46, v42, v46
	v_mul_f32_e32 v47, v43, v47
	v_cvt_pk_bf16_f32 v32, v36, v37
	v_cvt_pk_bf16_f32 v33, v38, v39
	v_cvt_pk_bf16_f32 v34, v44, v45
	v_cvt_pk_bf16_f32 v35, v46, v47
	s_nop 1
	v_permlane16_swap_b32_e32 v32, v34
	v_permlane16_swap_b32_e32 v33, v35
	global_store_dwordx4 v168, v[32:35], s[100:101] sc1
	s_add_u32 s100, s100, 0x16000
	s_addc_u32 s101, s101, 0
	v_mul_f32_e32 v160, 0xbfb8aa3b, v48
	v_mul_f32_e32 v161, 0xbfb8aa3b, v49
	v_mul_f32_e32 v162, 0xbfb8aa3b, v50
	v_mul_f32_e32 v163, 0xbfb8aa3b, v51
	v_mul_f32_e32 v164, 0xbfb8aa3b, v56
	v_mul_f32_e32 v165, 0xbfb8aa3b, v57
	v_mul_f32_e32 v166, 0xbfb8aa3b, v58
	v_mul_f32_e32 v167, 0xbfb8aa3b, v59
	v_exp_f32_e32 v160, v160
	v_exp_f32_e32 v161, v161
	v_exp_f32_e32 v162, v162
	v_exp_f32_e32 v163, v163
	v_exp_f32_e32 v164, v164
	v_exp_f32_e32 v165, v165
	v_exp_f32_e32 v166, v166
	v_exp_f32_e32 v167, v167
	v_add_f32_e32 v160, 1.0, v160
	v_add_f32_e32 v161, 1.0, v161
	v_add_f32_e32 v162, 1.0, v162
	v_add_f32_e32 v163, 1.0, v163
	v_add_f32_e32 v164, 1.0, v164
	v_add_f32_e32 v165, 1.0, v165
	v_add_f32_e32 v166, 1.0, v166
	v_add_f32_e32 v167, 1.0, v167
	v_rcp_f32_e32 v160, v160
	v_rcp_f32_e32 v161, v161
	v_rcp_f32_e32 v162, v162
	v_rcp_f32_e32 v163, v163
	v_rcp_f32_e32 v164, v164
	v_rcp_f32_e32 v165, v165
	v_rcp_f32_e32 v166, v166
	v_rcp_f32_e32 v167, v167
	v_mul_f32_e32 v48, v48, v160
	v_mul_f32_e32 v49, v49, v161
	v_mul_f32_e32 v50, v50, v162
	v_mul_f32_e32 v51, v51, v163
	v_mul_f32_e32 v56, v56, v164
	v_mul_f32_e32 v57, v57, v165
	v_mul_f32_e32 v58, v58, v166
	v_mul_f32_e32 v59, v59, v167
	v_mul_f32_e32 v52, v48, v52
	v_mul_f32_e32 v53, v49, v53
	v_mul_f32_e32 v54, v50, v54
	v_mul_f32_e32 v55, v51, v55
	v_mul_f32_e32 v60, v56, v60
	v_mul_f32_e32 v61, v57, v61
	v_mul_f32_e32 v62, v58, v62
	v_mul_f32_e32 v63, v59, v63
	v_cvt_pk_bf16_f32 v48, v52, v53
	v_cvt_pk_bf16_f32 v49, v54, v55
	v_cvt_pk_bf16_f32 v50, v60, v61
	v_cvt_pk_bf16_f32 v51, v62, v63
	s_nop 1
	v_permlane16_swap_b32_e32 v48, v50
	v_permlane16_swap_b32_e32 v49, v51
	global_store_dwordx4 v168, v[48:51], s[100:101] sc1
	s_add_u32 s100, s100, 0x16000
	s_addc_u32 s101, s101, 0
	v_mul_f32_e32 v160, 0xbfb8aa3b, v64
	v_mul_f32_e32 v161, 0xbfb8aa3b, v65
	v_mul_f32_e32 v162, 0xbfb8aa3b, v66
	v_mul_f32_e32 v163, 0xbfb8aa3b, v67
	v_mul_f32_e32 v164, 0xbfb8aa3b, v72
	v_mul_f32_e32 v165, 0xbfb8aa3b, v73
	v_mul_f32_e32 v166, 0xbfb8aa3b, v74
	v_mul_f32_e32 v167, 0xbfb8aa3b, v75
	v_exp_f32_e32 v160, v160
	v_exp_f32_e32 v161, v161
	v_exp_f32_e32 v162, v162
	v_exp_f32_e32 v163, v163
	v_exp_f32_e32 v164, v164
	v_exp_f32_e32 v165, v165
	v_exp_f32_e32 v166, v166
	v_exp_f32_e32 v167, v167
	v_add_f32_e32 v160, 1.0, v160
	v_add_f32_e32 v161, 1.0, v161
	v_add_f32_e32 v162, 1.0, v162
	v_add_f32_e32 v163, 1.0, v163
	v_add_f32_e32 v164, 1.0, v164
	v_add_f32_e32 v165, 1.0, v165
	v_add_f32_e32 v166, 1.0, v166
	v_add_f32_e32 v167, 1.0, v167
	v_rcp_f32_e32 v160, v160
	v_rcp_f32_e32 v161, v161
	v_rcp_f32_e32 v162, v162
	v_rcp_f32_e32 v163, v163
	v_rcp_f32_e32 v164, v164
	v_rcp_f32_e32 v165, v165
	v_rcp_f32_e32 v166, v166
	v_rcp_f32_e32 v167, v167
	v_mul_f32_e32 v64, v64, v160
	v_mul_f32_e32 v65, v65, v161
	v_mul_f32_e32 v66, v66, v162
	v_mul_f32_e32 v67, v67, v163
	v_mul_f32_e32 v72, v72, v164
	v_mul_f32_e32 v73, v73, v165
	v_mul_f32_e32 v74, v74, v166
	v_mul_f32_e32 v75, v75, v167
	v_mul_f32_e32 v68, v64, v68
	v_mul_f32_e32 v69, v65, v69
	v_mul_f32_e32 v70, v66, v70
	v_mul_f32_e32 v71, v67, v71
	v_mul_f32_e32 v76, v72, v76
	v_mul_f32_e32 v77, v73, v77
	v_mul_f32_e32 v78, v74, v78
	v_mul_f32_e32 v79, v75, v79
	v_cvt_pk_bf16_f32 v64, v68, v69
	v_cvt_pk_bf16_f32 v65, v70, v71
	v_cvt_pk_bf16_f32 v66, v76, v77
	v_cvt_pk_bf16_f32 v67, v78, v79
	s_nop 1
	v_permlane16_swap_b32_e32 v64, v66
	v_permlane16_swap_b32_e32 v65, v67
	global_store_dwordx4 v168, v[64:67], s[100:101] sc1
	s_add_u32 s100, s100, 0x16000
	s_addc_u32 s101, s101, 0
	v_mul_f32_e32 v160, 0xbfb8aa3b, v80
	v_mul_f32_e32 v161, 0xbfb8aa3b, v81
	v_mul_f32_e32 v162, 0xbfb8aa3b, v82
	v_mul_f32_e32 v163, 0xbfb8aa3b, v83
	v_mul_f32_e32 v164, 0xbfb8aa3b, v88
	v_mul_f32_e32 v165, 0xbfb8aa3b, v89
	v_mul_f32_e32 v166, 0xbfb8aa3b, v90
	v_mul_f32_e32 v167, 0xbfb8aa3b, v91
	v_exp_f32_e32 v160, v160
	v_exp_f32_e32 v161, v161
	v_exp_f32_e32 v162, v162
	v_exp_f32_e32 v163, v163
	v_exp_f32_e32 v164, v164
	v_exp_f32_e32 v165, v165
	v_exp_f32_e32 v166, v166
	v_exp_f32_e32 v167, v167
	v_add_f32_e32 v160, 1.0, v160
	v_add_f32_e32 v161, 1.0, v161
	v_add_f32_e32 v162, 1.0, v162
	v_add_f32_e32 v163, 1.0, v163
	v_add_f32_e32 v164, 1.0, v164
	v_add_f32_e32 v165, 1.0, v165
	v_add_f32_e32 v166, 1.0, v166
	v_add_f32_e32 v167, 1.0, v167
	v_rcp_f32_e32 v160, v160
	v_rcp_f32_e32 v161, v161
	v_rcp_f32_e32 v162, v162
	v_rcp_f32_e32 v163, v163
	v_rcp_f32_e32 v164, v164
	v_rcp_f32_e32 v165, v165
	v_rcp_f32_e32 v166, v166
	v_rcp_f32_e32 v167, v167
	v_mul_f32_e32 v80, v80, v160
	v_mul_f32_e32 v81, v81, v161
	v_mul_f32_e32 v82, v82, v162
	v_mul_f32_e32 v83, v83, v163
	v_mul_f32_e32 v88, v88, v164
	v_mul_f32_e32 v89, v89, v165
	v_mul_f32_e32 v90, v90, v166
	v_mul_f32_e32 v91, v91, v167
	v_mul_f32_e32 v84, v80, v84
	v_mul_f32_e32 v85, v81, v85
	v_mul_f32_e32 v86, v82, v86
	v_mul_f32_e32 v87, v83, v87
	v_mul_f32_e32 v92, v88, v92
	v_mul_f32_e32 v93, v89, v93
	v_mul_f32_e32 v94, v90, v94
	v_mul_f32_e32 v95, v91, v95
	v_cvt_pk_bf16_f32 v80, v84, v85
	v_cvt_pk_bf16_f32 v81, v86, v87
	v_cvt_pk_bf16_f32 v82, v92, v93
	v_cvt_pk_bf16_f32 v83, v94, v95
	s_nop 1
	v_permlane16_swap_b32_e32 v80, v82
	v_permlane16_swap_b32_e32 v81, v83
	global_store_dwordx4 v168, v[80:83], s[100:101] sc1
	s_add_u32 s100, s100, 0x16000
	s_addc_u32 s101, s101, 0
	v_mul_f32_e32 v160, 0xbfb8aa3b, v96
	v_mul_f32_e32 v161, 0xbfb8aa3b, v97
	v_mul_f32_e32 v162, 0xbfb8aa3b, v98
	v_mul_f32_e32 v163, 0xbfb8aa3b, v99
	v_mul_f32_e32 v164, 0xbfb8aa3b, v104
	v_mul_f32_e32 v165, 0xbfb8aa3b, v105
	v_mul_f32_e32 v166, 0xbfb8aa3b, v106
	v_mul_f32_e32 v167, 0xbfb8aa3b, v107
	v_exp_f32_e32 v160, v160
	v_exp_f32_e32 v161, v161
	v_exp_f32_e32 v162, v162
	v_exp_f32_e32 v163, v163
	v_exp_f32_e32 v164, v164
	v_exp_f32_e32 v165, v165
	v_exp_f32_e32 v166, v166
	v_exp_f32_e32 v167, v167
	v_add_f32_e32 v160, 1.0, v160
	v_add_f32_e32 v161, 1.0, v161
	v_add_f32_e32 v162, 1.0, v162
	v_add_f32_e32 v163, 1.0, v163
	v_add_f32_e32 v164, 1.0, v164
	v_add_f32_e32 v165, 1.0, v165
	v_add_f32_e32 v166, 1.0, v166
	v_add_f32_e32 v167, 1.0, v167
	v_rcp_f32_e32 v160, v160
	v_rcp_f32_e32 v161, v161
	v_rcp_f32_e32 v162, v162
	v_rcp_f32_e32 v163, v163
	v_rcp_f32_e32 v164, v164
	v_rcp_f32_e32 v165, v165
	v_rcp_f32_e32 v166, v166
	v_rcp_f32_e32 v167, v167
	v_mul_f32_e32 v96, v96, v160
	v_mul_f32_e32 v97, v97, v161
	v_mul_f32_e32 v98, v98, v162
	v_mul_f32_e32 v99, v99, v163
	v_mul_f32_e32 v104, v104, v164
	v_mul_f32_e32 v105, v105, v165
	v_mul_f32_e32 v106, v106, v166
	v_mul_f32_e32 v107, v107, v167
	v_mul_f32_e32 v100, v96, v100
	v_mul_f32_e32 v101, v97, v101
	v_mul_f32_e32 v102, v98, v102
	v_mul_f32_e32 v103, v99, v103
	v_mul_f32_e32 v108, v104, v108
	v_mul_f32_e32 v109, v105, v109
	v_mul_f32_e32 v110, v106, v110
	v_mul_f32_e32 v111, v107, v111
	v_cvt_pk_bf16_f32 v96, v100, v101
	v_cvt_pk_bf16_f32 v97, v102, v103
	v_cvt_pk_bf16_f32 v98, v108, v109
	v_cvt_pk_bf16_f32 v99, v110, v111
	s_nop 1
	v_permlane16_swap_b32_e32 v96, v98
	v_permlane16_swap_b32_e32 v97, v99
	global_store_dwordx4 v168, v[96:99], s[100:101] sc1
	s_add_u32 s100, s100, 0x16000
	s_addc_u32 s101, s101, 0
	v_mul_f32_e32 v160, 0xbfb8aa3b, v112
	v_mul_f32_e32 v161, 0xbfb8aa3b, v113
	v_mul_f32_e32 v162, 0xbfb8aa3b, v114
	v_mul_f32_e32 v163, 0xbfb8aa3b, v115
	v_mul_f32_e32 v164, 0xbfb8aa3b, v120
	v_mul_f32_e32 v165, 0xbfb8aa3b, v121
	v_mul_f32_e32 v166, 0xbfb8aa3b, v122
	v_mul_f32_e32 v167, 0xbfb8aa3b, v123
	v_exp_f32_e32 v160, v160
	v_exp_f32_e32 v161, v161
	v_exp_f32_e32 v162, v162
	v_exp_f32_e32 v163, v163
	v_exp_f32_e32 v164, v164
	v_exp_f32_e32 v165, v165
	v_exp_f32_e32 v166, v166
	v_exp_f32_e32 v167, v167
	v_add_f32_e32 v160, 1.0, v160
	v_add_f32_e32 v161, 1.0, v161
	v_add_f32_e32 v162, 1.0, v162
	v_add_f32_e32 v163, 1.0, v163
	v_add_f32_e32 v164, 1.0, v164
	v_add_f32_e32 v165, 1.0, v165
	v_add_f32_e32 v166, 1.0, v166
	v_add_f32_e32 v167, 1.0, v167
	v_rcp_f32_e32 v160, v160
	v_rcp_f32_e32 v161, v161
	v_rcp_f32_e32 v162, v162
	v_rcp_f32_e32 v163, v163
	v_rcp_f32_e32 v164, v164
	v_rcp_f32_e32 v165, v165
	v_rcp_f32_e32 v166, v166
	v_rcp_f32_e32 v167, v167
	v_mul_f32_e32 v112, v112, v160
	v_mul_f32_e32 v113, v113, v161
	v_mul_f32_e32 v114, v114, v162
	v_mul_f32_e32 v115, v115, v163
	v_mul_f32_e32 v120, v120, v164
	v_mul_f32_e32 v121, v121, v165
	v_mul_f32_e32 v122, v122, v166
	v_mul_f32_e32 v123, v123, v167
	v_mul_f32_e32 v116, v112, v116
	v_mul_f32_e32 v117, v113, v117
	v_mul_f32_e32 v118, v114, v118
	v_mul_f32_e32 v119, v115, v119
	v_mul_f32_e32 v124, v120, v124
	v_mul_f32_e32 v125, v121, v125
	v_mul_f32_e32 v126, v122, v126
	v_mul_f32_e32 v127, v123, v127
	v_cvt_pk_bf16_f32 v112, v116, v117
	v_cvt_pk_bf16_f32 v113, v118, v119
	v_cvt_pk_bf16_f32 v114, v124, v125
	v_cvt_pk_bf16_f32 v115, v126, v127
	s_nop 1
	v_permlane16_swap_b32_e32 v112, v114
	v_permlane16_swap_b32_e32 v113, v115
	global_store_dwordx4 v168, v[112:115], s[100:101] sc1
	s_and_b64 vcc, exec, s[16:17]
	s_mov_b32 s22, s18
	s_mov_b32 s24, s20
	s_mov_b64 s[10:11], s[26:27]
	s_mov_b64 s[12:13], s[46:47]
	s_mov_b32 s36, s39
	s_cbranch_vccz .Lgl_tile_f0

.LBB0_1443:
	s_cmp_lt_i32 s88, 16
	s_cselect_b64 s[6:7], -1, 0
	s_and_b64 s[4:5], s[6:7], s[4:5]
	s_andn2_b64 vcc, exec, s[4:5]
	s_cbranch_vccnz .LBB0_1451
	s_cmpk_gt_i32 s2, 0x2bf
	s_cbranch_scc1 .LBB0_1451
	s_add_u32 s8, s34, 0x28c4000
	s_addc_u32 s9, s35, 0
	s_add_u32 s14, s34, 0x8a44000
	s_addc_u32 s15, s35, 0
	s_add_u32 s28, s34, 0x12a0000
	s_addc_u32 s29, s35, 0
	s_load_dword s31, s[0:1], 0x120
	v_readfirstlane_b32 s37, v205
	v_and_b32_e32 v192, 15, v204
	v_bfe_u32 v193, v204, 4, 2
	v_lshrrev_b32_e32 v194, 8, v204
	v_bfe_u32 v195, v204, 6, 2
	v_bfe_u32 v196, v204, 1, 3
	v_xor_b32_e32 v197, v193, v196
	v_xor_b32_e32 v198, 4, v197
	v_lshlrev_b32_e32 v197, 4, v197
	v_lshlrev_b32_e32 v198, 4, v198
	v_lshlrev_b32_e32 v199, 14, v194
	v_lshl_add_u32 v199, v192, 7, v199
	v_add_u32_e32 v242, v199, v197
	v_add_u32_e32 v243, v199, v198
	v_lshlrev_b32_e32 v199, 13, v195
	v_lshl_add_u32 v199, v192, 7, v199
	v_add_u32_e32 v199, 0x8000, v199
	v_add_u32_e32 v244, v199, v197
	v_add_u32_e32 v245, v199, v198
	v_add_u32_e32 v246, 0x10000, v242
	v_add_u32_e32 v248, 0x10000, v244
	v_add_u32_e32 v247, 0x10000, v243
	v_add_u32_e32 v249, 0x10000, v245
	v_lshrrev_b32_e32 v199, 3, v204
	v_and_b32_e32 v200, 7, v204
	v_bfe_u32 v201, v204, 4, 3
	v_xor_b32_e32 v200, v200, v201
	v_lshlrev_b32_e32 v200, 4, v200
	v_lshl_add_u32 v238, v199, 11, v200
	v_add_u32_e32 v239, 0x20000, v238
	v_add_u32_e32 v240, 0x40000, v238
	v_add_u32_e32 v241, 0x60000, v238
	s_lshl_b32 s38, s37, 10
	s_mov_b32 s36, s2
	s_and_b32 s4, s36, 7
	s_mulk_i32 s4, 0x58
	s_lshr_b32 s5, s36, 3
	s_add_i32 s4, s4, s5
	s_cmpk_ge_i32 s4, 176
	s_cselect_b32 s5, 1, 0
	s_cmpk_ge_i32 s4, 352
	s_cselect_b32 s19, 1, 0
	s_add_i32 s5, s5, s19
	s_cmpk_ge_i32 s4, 528
	s_cselect_b32 s19, 1, 0
	s_add_i32 s5, s5, s19
	s_mul_i32 s19, s5, 176
	s_sub_i32 s4, s4, s19
	s_and_b32 s19, s4, 7
	s_lshl_b32 s5, s5, 3
	s_add_i32 s5, s5, s19
	s_lshl_b32 s22, s5, 8
	s_lshr_b32 s4, s4, 3
	s_lshl_b32 s24, s4, 8
	s_lshl_b32 s19, s22, 11
	s_add_u32 s10, s14, s19
	s_addc_u32 s11, s15, 0
	s_lshl_b32 s19, s24, 11
	s_add_u32 s12, s28, s19
	s_addc_u32 s13, s29, 0
	s_waitcnt vmcnt(0) lgkmcnt(0)
	s_barrier
	s_add_u32 m0, s38, 0x0
	s_nop 0
	global_load_lds_dwordx4 v238, s[10:11]
	s_add_u32 m0, s38, 0x2000
	s_nop 0
	global_load_lds_dwordx4 v239, s[10:11]
	s_add_u32 m0, s38, 0x4000
	s_nop 0
	global_load_lds_dwordx4 v240, s[10:11]
	s_add_u32 m0, s38, 0x6000
	s_nop 0
	global_load_lds_dwordx4 v241, s[10:11]
	s_add_u32 m0, s38, 0x8000
	s_nop 0
	global_load_lds_dwordx4 v238, s[12:13]
	s_add_u32 m0, s38, 0xa000
	s_nop 0
	global_load_lds_dwordx4 v239, s[12:13]
	s_add_u32 m0, s38, 0xc000
	s_nop 0
	global_load_lds_dwordx4 v240, s[12:13]
	s_add_u32 m0, s38, 0xe000
	s_nop 0
	global_load_lds_dwordx4 v241, s[12:13]
	s_waitcnt vmcnt(0)
